# attention: odd-head waves take the other row half so SIMD partners never both run the half-masked last key tile
# speedup vs baseline: 1.0005x; 1.0005x over previous
.LBB0_877:
	s_or_b64 exec, exec, s[0:1]
	v_lshrrev_b32_e32 v244, 1, v254
	v_and_b32_e32 v244, 0x80, v244
	v_xor_b32_e32 v244, v244, v254
	v_mov_b32_e32 v1, v244
	s_waitcnt lgkmcnt(0)
	s_barrier
	s_cmp_lg_u32 0, -1
	v_lshrrev_b32_e32 v5, 2, v1
	v_lshrrev_b32_e32 v2, 5, v1
	v_lshlrev_b32_e32 v4, 2, v1
	v_and_b32_e32 v6, 2, v5
	v_and_or_b32 v4, v4, 12, v6
	v_xor_b32_e32 v6, v2, v5
	v_and_or_b32 v4, v6, 1, v4
	v_lshrrev_b32_e32 v6, 1, v1
	v_and_b32_e32 v0, 31, v1
	v_xor_b32_e32 v2, v2, v6
	v_lshlrev_b32_e32 v7, 7, v0
	v_lshlrev_b32_e32 v2, 4, v2
	v_lshlrev_b32_e32 v6, 3, v1
	v_bfe_u32 v3, v1, 5, 1
	v_and_or_b32 v2, v2, 16, v7
	v_and_b32_e32 v7, 0x60, v6
	v_bfe_u32 v8, v1, 2, 2
	v_and_b32_e32 v6, 8, v6
	s_cselect_b32 s0, 0, 0
	v_lshrrev_b32_e32 v9, 3, v1
	v_lshlrev_b32_e32 v12, 10, v3
	v_lshlrev_b32_e32 v13, 8, v8
	v_add_u32_e32 v6, s0, v6
	v_and_b32_e32 v10, 2, v9
	v_bfe_u32 v11, v1, 1, 1
	v_add3_u32 v6, v6, v12, v13
	v_or_b32_e32 v13, 2, v3
	v_lshlrev_b32_e32 v0, 8, v0
	v_bitop3_b32 v12, v10, v3, v11 bitop3:0x36
	v_bitop3_b32 v10, v10, v13, v11 bitop3:0x36
	v_lshl_or_b32 v198, v4, 4, v0
	v_lshlrev_b32_e32 v0, 4, v1
	v_lshlrev_b32_e32 v10, 4, v10
	s_movk_i32 s0, 0x800
	v_lshlrev_b32_e32 v8, 6, v8
	s_movk_i32 s16, 0x4000
	v_and_b32_e32 v0, 0x1f0, v0
	v_lshl_add_u32 v12, v12, 4, v6
	v_add3_u32 v6, v6, v10, s0
	v_xor_b32_e32 v10, 64, v8
	v_or3_b32 v199, v2, v7, s16
	v_lshl_or_b32 v2, v3, 9, v0
	v_mov_b32_e32 v0, 0
	v_add_u32_e32 v188, v12, v8
	v_add_u32_e32 v189, v6, v8
	v_add_u32_e32 v192, v12, v10
	v_add_u32_e32 v193, v6, v10
	v_xor_b32_e32 v10, 0x80, v8
	v_xor_b32_e32 v8, 0xc0, v8
	v_mov_b32_e32 v3, v0
	v_add_u32_e32 v196, v12, v8
	v_add_u32_e32 v197, v6, v8
	v_lshl_add_u64 v[162:163], s[36:37], 0, v[2:3]
	v_and_b32_e32 v2, 15, v1
	v_and_b32_e32 v5, 12, v5
	v_bfe_u32 v8, v1, 6, 2
	v_bitop3_b32 v2, v5, v2, v8 bitop3:0x36
	s_not_b32 s0, s2
	v_add_u32_e32 v3, 0x200, v1
	v_lshrrev_b32_e32 v4, 4, v1
	v_lshlrev_b32_e32 v2, 4, v2
	s_movk_i32 s7, 0x180
	s_add_i32 s17, s30, s0
	v_mad_u64_u32 v[164:165], s[0:1], v4, s7, v[2:3]
	v_bfe_u32 v7, v1, 4, 5
	v_lshrrev_b32_e32 v5, 4, v3
	s_mov_b32 s0, 0x1ffffe0
	v_add_u32_e32 v195, v6, v10
	s_movk_i32 s6, 0xc0
	v_ashrrev_i32_e32 v6, 6, v1
	v_ashrrev_i32_e32 v200, 8, v1
	v_and_or_b32 v5, v5, s0, v7
	v_xor_b32_e32 v1, v4, v1
	v_mad_u64_u32 v[166:167], s[0:1], v5, s7, v[2:3]
	v_mul_lo_u32 v5, v9, s6
	v_lshlrev_b32_e32 v1, 3, v1
	v_and_or_b32 v1, v1, 56, v5
	v_mov_b32_e32 v5, 0x100
	v_lshlrev_b32_e32 v4, 10, v6
	v_lshl_add_u32 v168, v1, 1, v5
	v_lshrrev_b32_e32 v1, 9, v3
	v_mul_u32_u24_e32 v1, 0x3000, v1
	v_mul_u32_u24_e32 v3, 0x180, v7
	v_add_u32_e32 v203, 0, v4
	s_mov_b32 s3, 0
	v_add_u32_e32 v194, v12, v10
	v_and_b32_e32 v201, 3, v6
	v_bfe_u32 v202, v6, 1, 1
	v_mov_b32_e32 v165, v0
	v_mov_b32_e32 v167, v0
	v_mov_b32_e32 v169, v0
	s_movk_i32 s36, 0x3000
	v_add3_u32 v170, v1, v3, v2
	v_mov_b32_e32 v171, v0
	s_movk_i32 s37, 0x1000
	s_movk_i32 s40, 0x2000
	v_add_u32_e32 v204, 0x2000, v203
	v_add_u32_e32 v205, 0x4000, v203
	s_mov_b64 s[0:1], 0x1dc06000
	s_mov_b32 s41, 0x8000
	s_mov_b64 s[6:7], 0x1dc0c000
	s_movk_i32 s44, 0xfe0
	s_movk_i32 s45, 0x2200
	s_mov_b32 s50, 0xc000
	s_mov_b32 s51, 0x10000
	s_mov_b32 s52, 0x14000
	s_mov_b32 s53, 0x18000
	v_mbcnt_hi_u32_b32 v191, -1, v186
	v_readfirstlane_b32 s74, v203
	v_readfirstlane_b32 s76, v244
	s_nop 0
	s_bfe_u32 s76, s76, 0x10007
	s_mov_b32 s54, 0
	s_branch .LBB0_879

.LBB0_893:
	v_mov_b32_e32 v1, v244
	v_lshlrev_b32_e32 v98, 5, v206
	v_bfe_u32 v157, v1, 5, 1
	v_and_b32_e32 v156, 31, v1
	v_lshlrev_b32_e32 v66, 9, v157
	v_mov_b32_e32 v67, v0
	v_lshl_add_u64 v[66:67], s[38:39], 0, v[66:67]
	v_lshlrev_b32_e32 v68, 4, v156
	v_mov_b32_e32 v69, v0
	v_ashrrev_i32_e32 v99, 31, v98
	v_lshl_add_u64 v[100:101], v[66:67], 0, v[68:69]
	v_lshlrev_b64 v[66:67], 10, v[98:99]
	v_lshl_add_u64 v[74:75], v[100:101], 0, v[66:67]
	global_load_dwordx4 v[66:69], v[74:75], off
	v_or_b32_e32 v70, 8, v98
	v_ashrrev_i32_e32 v71, 31, v70
	v_lshlrev_b64 v[70:71], 10, v[70:71]
	v_lshl_add_u64 v[76:77], v[100:101], 0, v[70:71]
	global_load_dwordx4 v[70:73], v[76:77], off
	global_load_dwordx4 v[102:105], v[74:75], off offset:1024
	global_load_dwordx4 v[106:109], v[76:77], off offset:1024
	global_load_dwordx4 v[110:113], v[74:75], off offset:2048
	global_load_dwordx4 v[114:117], v[76:77], off offset:2048
	global_load_dwordx4 v[118:121], v[74:75], off offset:3072
	v_and_b32_e32 v79, 64, v191
	v_xor_b32_e32 v78, 32, v191
	v_add_u32_e32 v79, 64, v79
	v_cmp_lt_i32_e32 vcc, v78, v79
	global_load_dwordx4 v[122:125], v[76:77], off offset:3072
	v_ashrrev_i32_e32 v158, 6, v1
	v_cndmask_b32_e32 v78, v191, v78, vcc
	v_lshlrev_b32_e32 v78, 2, v78
	ds_bpermute_b32 v78, v78, v173
	v_add_co_u32_e32 v134, vcc, s37, v74
	v_bfe_u32 v160, v1, 4, 2
	s_nop 0
	v_addc_co_u32_e32 v135, vcc, 0, v75, vcc
	s_waitcnt lgkmcnt(0)
	v_add_f32_e32 v74, v173, v78
	v_div_scale_f32 v75, s[8:9], v74, v74, 1.0
	v_add_co_u32_e32 v136, vcc, s37, v76
	global_load_dwordx4 v[126:129], v[134:135], off
	v_rcp_f32_e32 v76, v75
	v_addc_co_u32_e32 v137, vcc, 0, v77, vcc
	v_div_scale_f32 v77, vcc, 1.0, v74, 1.0
	v_fma_f32 v78, -v75, v76, 1.0
	v_fmac_f32_e32 v76, v78, v76
	v_mul_f32_e32 v78, v77, v76
	v_fma_f32 v79, -v75, v78, v77
	v_fmac_f32_e32 v78, v79, v76
	v_fma_f32 v75, -v75, v78, v77
	v_div_fmas_f32 v75, v75, v76, v78
	v_div_fixup_f32 v138, v75, v74, 1.0
	v_pk_mul_f32 v[50:51], v[50:51], v[138:139] op_sel_hi:[1,0]
	v_pk_mul_f32 v[52:53], v[52:53], v[138:139] op_sel_hi:[1,0]
	v_pk_mul_f32 v[54:55], v[54:55], v[138:139] op_sel_hi:[1,0]
	v_pk_mul_f32 v[56:57], v[56:57], v[138:139] op_sel_hi:[1,0]
	v_cvt_pk_bf16_f32 v50, v50, v51
	v_cvt_pk_bf16_f32 v51, v52, v53
	v_cvt_pk_bf16_f32 v52, v54, v55
	v_cvt_pk_bf16_f32 v53, v56, v57
	global_load_dwordx4 v[54:57], v[136:137], off
	global_load_dwordx4 v[130:133], v[134:135], off offset:1024
	v_pk_mul_f32 v[58:59], v[58:59], v[138:139] op_sel_hi:[1,0]
	v_pk_mul_f32 v[60:61], v[60:61], v[138:139] op_sel_hi:[1,0]
	v_pk_mul_f32 v[62:63], v[62:63], v[138:139] op_sel_hi:[1,0]
	v_pk_mul_f32 v[64:65], v[64:65], v[138:139] op_sel_hi:[1,0]
	v_cvt_pk_bf16_f32 v58, v58, v59
	v_cvt_pk_bf16_f32 v59, v60, v61
	v_cvt_pk_bf16_f32 v60, v62, v63
	v_cvt_pk_bf16_f32 v61, v64, v65
	v_pk_mul_f32 v[34:35], v[34:35], v[138:139] op_sel_hi:[1,0]
	v_pk_mul_f32 v[36:37], v[36:37], v[138:139] op_sel_hi:[1,0]
	v_pk_mul_f32 v[38:39], v[38:39], v[138:139] op_sel_hi:[1,0]
	v_pk_mul_f32 v[40:41], v[40:41], v[138:139] op_sel_hi:[1,0]
	v_pk_mul_f32 v[42:43], v[42:43], v[138:139] op_sel_hi:[1,0]
	v_pk_mul_f32 v[44:45], v[44:45], v[138:139] op_sel_hi:[1,0]
	v_pk_mul_f32 v[46:47], v[46:47], v[138:139] op_sel_hi:[1,0]
	v_pk_mul_f32 v[48:49], v[48:49], v[138:139] op_sel_hi:[1,0]
	v_pk_mul_f32 v[18:19], v[18:19], v[138:139] op_sel_hi:[1,0]
	v_pk_mul_f32 v[20:21], v[20:21], v[138:139] op_sel_hi:[1,0]
	v_pk_mul_f32 v[22:23], v[22:23], v[138:139] op_sel_hi:[1,0]
	v_pk_mul_f32 v[24:25], v[24:25], v[138:139] op_sel_hi:[1,0]
	v_pk_mul_f32 v[26:27], v[26:27], v[138:139] op_sel_hi:[1,0]
	v_pk_mul_f32 v[28:29], v[28:29], v[138:139] op_sel_hi:[1,0]
	v_pk_mul_f32 v[30:31], v[30:31], v[138:139] op_sel_hi:[1,0]
	v_pk_mul_f32 v[32:33], v[32:33], v[138:139] op_sel_hi:[1,0]
	v_pk_mul_f32 v[2:3], v[2:3], v[138:139] op_sel_hi:[1,0]
	v_pk_mul_f32 v[4:5], v[4:5], v[138:139] op_sel_hi:[1,0]
	s_waitcnt vmcnt(10)
	v_mfma_f32_32x32x16_bf16 v[82:97], v[66:69], v[50:53], 0
	v_mul_f32_e64 v6, v6, v138
	v_mul_f32_e64 v7, v7, v138
	v_mul_f32_e64 v8, v8, v138
	v_mul_f32_e64 v9, v9, v138
	v_mul_f32_e64 v10, v10, v138
	v_mul_f32_e64 v11, v11, v138
	v_ashrrev_i32_e32 v173, 31, v172
	v_lshlrev_b32_e32 v1, 4, v1
	v_and_b32_e32 v154, 0xf0, v1
	v_mov_b32_e32 v155, v0
	s_waitcnt vmcnt(9)
	v_mfma_f32_32x32x16_bf16 v[66:81], v[70:73], v[50:53], 0
	v_mul_lo_u32 v1, v158, s45
	v_add_u32_e32 v1, 0, v1
	s_mov_b32 s14, 0
	s_waitcnt vmcnt(8)
	v_mfma_f32_32x32x16_bf16 v[82:97], v[102:105], v[58:61], v[82:97]
	global_load_dwordx4 v[62:65], v[134:135], off offset:2048
	global_load_dwordx4 v[102:105], v[134:135], off offset:3072
	s_waitcnt vmcnt(9)
	v_mfma_f32_32x32x16_bf16 v[66:81], v[106:109], v[58:61], v[66:81]
	v_cvt_pk_bf16_f32 v106, v34, v35
	v_cvt_pk_bf16_f32 v107, v36, v37
	v_cvt_pk_bf16_f32 v108, v38, v39
	v_cvt_pk_bf16_f32 v109, v40, v41
	global_load_dwordx4 v[34:37], v[136:137], off offset:1024
	global_load_dwordx4 v[38:41], v[136:137], off offset:2048
	s_waitcnt vmcnt(10)
	v_mfma_f32_32x32x16_bf16 v[82:97], v[110:113], v[106:109], v[82:97]
	v_cvt_pk_bf16_f32 v110, v42, v43
	v_cvt_pk_bf16_f32 v111, v44, v45
	global_load_dwordx4 v[42:45], v[136:137], off offset:3072
	v_cvt_pk_bf16_f32 v112, v46, v47
	v_or_b32_e32 v46, 16, v98
	v_ashrrev_i32_e32 v47, 31, v46
	v_lshlrev_b64 v[46:47], 10, v[46:47]
	v_lshl_add_u64 v[134:135], v[100:101], 0, v[46:47]
	s_waitcnt vmcnt(10)
	v_mfma_f32_32x32x16_bf16 v[66:81], v[114:117], v[106:109], v[66:81]
	v_cvt_pk_bf16_f32 v113, v48, v49
	v_cvt_pk_bf16_f32 v114, v18, v19
	v_cvt_pk_bf16_f32 v115, v20, v21
	v_cvt_pk_bf16_f32 v116, v22, v23
	v_cvt_pk_bf16_f32 v117, v24, v25
	global_load_dwordx4 v[18:21], v[134:135], off
	global_load_dwordx4 v[22:25], v[134:135], off offset:1024
	global_load_dwordx4 v[46:49], v[134:135], off offset:2048
	s_waitcnt vmcnt(12)
	v_mfma_f32_32x32x16_bf16 v[82:97], v[118:121], v[110:113], v[82:97]
	v_cvt_pk_bf16_f32 v118, v26, v27
	v_cvt_pk_bf16_f32 v119, v28, v29
	v_cvt_pk_bf16_f32 v120, v30, v31
	v_cvt_pk_bf16_f32 v121, v32, v33
	global_load_dwordx4 v[26:29], v[134:135], off offset:3072
	s_waitcnt vmcnt(12)
	v_mfma_f32_32x32x16_bf16 v[66:81], v[122:125], v[110:113], v[66:81]
	v_cvt_pk_bf16_f32 v122, v2, v3
	v_cvt_pk_bf16_f32 v123, v4, v5
	v_cvt_pk_bf16_f32 v124, v6, v7
	v_cvt_pk_bf16_f32 v125, v8, v9
	v_mul_f32_e64 v2, v12, v138
	v_mul_f32_e64 v3, v13, v138
	v_pk_mul_f32 v[4:5], v[14:15], v[138:139] op_sel_hi:[1,0]
	v_pk_mul_f32 v[6:7], v[16:17], v[138:139] op_sel_hi:[1,0]
	s_waitcnt vmcnt(11)
	v_mfma_f32_32x32x16_bf16 v[82:97], v[126:129], v[114:117], v[82:97]
	s_waitcnt vmcnt(10)
	v_mfma_f32_32x32x16_bf16 v[66:81], v[54:57], v[114:117], v[66:81]
	s_waitcnt vmcnt(9)
	v_mfma_f32_32x32x16_bf16 v[82:97], v[130:133], v[118:121], v[82:97]
	s_waitcnt vmcnt(6)
	v_mfma_f32_32x32x16_bf16 v[66:81], v[34:37], v[118:121], v[66:81]
	v_mfma_f32_32x32x16_bf16 v[82:97], v[62:65], v[122:125], v[82:97]
	v_cvt_pk_bf16_f32 v63, v2, v3
	v_add_co_u32_e32 v2, vcc, s37, v134
	v_cvt_pk_bf16_f32 v62, v10, v11
	s_nop 0
	v_addc_co_u32_e32 v3, vcc, 0, v135, vcc
	global_load_dwordx4 v[30:33], v[2:3], off
	global_load_dwordx4 v[34:37], v[2:3], off offset:1024
	s_waitcnt vmcnt(7)
	v_mfma_f32_32x32x16_bf16 v[66:81], v[38:41], v[122:125], v[66:81]
	v_cvt_pk_bf16_f32 v64, v4, v5
	v_cvt_pk_bf16_f32 v65, v6, v7
	s_waitcnt vmcnt(6)
	s_nop 0
	v_mfma_f32_32x32x16_bf16 v[66:81], v[42:45], v[62:65], v[66:81]
	global_load_dwordx4 v[38:41], v[2:3], off offset:2048
	global_load_dwordx4 v[42:45], v[2:3], off offset:3072
	s_waitcnt vmcnt(7)
	v_mfma_f32_32x32x16_bf16 v[2:17], v[18:21], v[50:53], 0
	v_or_b32_e32 v18, 24, v98
	v_ashrrev_i32_e32 v19, 31, v18
	v_lshlrev_b64 v[18:19], 10, v[18:19]
	v_lshl_add_u64 v[54:55], v[100:101], 0, v[18:19]
	global_load_dwordx4 v[18:21], v[54:55], off
	global_load_dwordx4 v[98:101], v[54:55], off offset:1024
	v_mfma_f32_32x32x16_bf16 v[82:97], v[102:105], v[62:65], v[82:97]
	global_load_dwordx4 v[102:105], v[54:55], off offset:2048
	global_load_dwordx4 v[126:129], v[54:55], off offset:3072
	s_waitcnt vmcnt(10)
	v_mfma_f32_32x32x16_bf16 v[2:17], v[22:25], v[58:61], v[2:17]
	v_add_co_u32_e32 v22, vcc, s37, v54
	v_mov_b32_e32 v24, s55
	s_nop 0
	v_addc_co_u32_e32 v23, vcc, 0, v55, vcc
	global_load_dwordx4 v[130:133], v[22:23], off
	global_load_dwordx4 v[134:137], v[22:23], off offset:1024
	global_load_dwordx4 v[138:141], v[22:23], off offset:2048
	global_load_dwordx4 v[142:145], v[22:23], off offset:3072
	s_waitcnt vmcnt(13)
	v_mfma_f32_32x32x16_bf16 v[2:17], v[46:49], v[106:109], v[2:17]
	v_lshlrev_b32_e32 v22, 5, v158
	v_and_b32_e32 v159, 0x60, v22
	v_lshlrev_b64 v[22:23], 12, v[172:173]
	v_bitop3_b32 v24, v159, s44, v24 bitop3:0xc8
	v_or3_b32 v22, v22, v24, v160
	v_lshlrev_b64 v[22:23], 8, v[22:23]
	s_waitcnt vmcnt(12)
	v_mfma_f32_32x32x16_bf16 v[2:17], v[26:29], v[110:113], v[2:17]
	s_waitcnt vmcnt(11)
	v_mfma_f32_32x32x16_bf16 v[2:17], v[30:33], v[114:117], v[2:17]
	s_waitcnt vmcnt(10)
	v_mfma_f32_32x32x16_bf16 v[2:17], v[34:37], v[118:121], v[2:17]
	v_lshl_add_u64 v[34:35], s[22:23], 0, v[22:23]
	v_lshl_add_u64 v[34:35], v[34:35], 0, v[154:155]
	s_waitcnt vmcnt(7)
	v_mfma_f32_32x32x16_bf16 v[18:33], v[18:21], v[50:53], 0
	global_load_dwordx4 v[146:149], v[34:35], off
	global_load_dwordx4 v[150:153], v[34:35], off offset:1024
	global_load_dwordx4 v[54:57], v[34:35], off offset:2048
	global_load_dwordx4 v[50:53], v[34:35], off offset:3072
	v_add_co_u32_e32 v34, vcc, s37, v34
	s_nop 1
	v_addc_co_u32_e32 v35, vcc, 0, v35, vcc
	s_waitcnt vmcnt(10)
	v_mfma_f32_32x32x16_bf16 v[18:33], v[98:101], v[58:61], v[18:33]
	v_mul_u32_u24_e32 v98, 0x110, v156
	v_lshlrev_b32_e32 v99, 5, v157
	v_cvt_pk_f16_f32 v58, v82, v83
	v_add3_u32 v82, v1, v98, v99
	v_cvt_pk_f16_f32 v59, v84, v85
	v_cvt_pk_f16_f32 v60, v86, v87
	v_cvt_pk_f16_f32 v61, v88, v89
	s_waitcnt vmcnt(9)
	v_mfma_f32_32x32x16_bf16 v[18:33], v[102:105], v[106:109], v[18:33]
	s_waitcnt vmcnt(8)
	v_mfma_f32_32x32x16_bf16 v[18:33], v[126:129], v[110:113], v[18:33]
	s_waitcnt vmcnt(7)
	v_mfma_f32_32x32x16_bf16 v[18:33], v[130:133], v[114:117], v[18:33]
	s_waitcnt vmcnt(6)
	v_mfma_f32_32x32x16_bf16 v[18:33], v[134:137], v[118:121], v[18:33]
	v_mfma_f32_32x32x16_bf16 v[2:17], v[38:41], v[122:125], v[2:17]
	s_waitcnt vmcnt(5)
	v_mfma_f32_32x32x16_bf16 v[18:33], v[138:141], v[122:125], v[18:33]
	v_mfma_f32_32x32x16_bf16 v[2:17], v[42:45], v[62:65], v[2:17]
	global_load_dwordx4 v[46:49], v[34:35], off
	global_load_dwordx4 v[42:45], v[34:35], off offset:1024
	global_load_dwordx4 v[38:41], v[34:35], off offset:2048
	s_nop 0
	global_load_dwordx4 v[34:37], v[34:35], off offset:3072
	ds_write_b128 v82, v[58:61] offset:49152
	v_cvt_pk_f16_f32 v58, v90, v91
	v_cvt_pk_f16_f32 v59, v92, v93
	v_cvt_pk_f16_f32 v60, v94, v95
	v_cvt_pk_f16_f32 v61, v96, v97
	ds_write_b128 v82, v[58:61] offset:49168
	s_waitcnt vmcnt(8)
	v_mfma_f32_32x32x16_bf16 v[18:33], v[142:145], v[62:65], v[18:33]
	v_cvt_pk_f16_f32 v2, v2, v3
	v_cvt_pk_f16_f32 v3, v4, v5
	v_cvt_pk_f16_f32 v4, v6, v7
	v_cvt_pk_f16_f32 v5, v8, v9
	ds_write_b128 v82, v[2:5] offset:49280
	v_cvt_pk_f16_f32 v2, v10, v11
	v_cvt_pk_f16_f32 v3, v12, v13
	v_cvt_pk_f16_f32 v4, v14, v15
	v_cvt_pk_f16_f32 v5, v16, v17
	ds_write_b128 v82, v[2:5] offset:49296
	s_nop 1
	v_cvt_pk_f16_f32 v2, v18, v19
	v_cvt_pk_f16_f32 v3, v20, v21
	v_cvt_pk_f16_f32 v4, v22, v23
	v_cvt_pk_f16_f32 v5, v24, v25
	v_cvt_pk_f16_f32 v58, v66, v67
	v_cvt_pk_f16_f32 v59, v68, v69
	v_cvt_pk_f16_f32 v60, v70, v71
	v_cvt_pk_f16_f32 v61, v72, v73
	ds_write_b128 v82, v[2:5] offset:49344
	v_cvt_pk_f16_f32 v2, v26, v27
	v_cvt_pk_f16_f32 v3, v28, v29
	v_cvt_pk_f16_f32 v4, v30, v31
	v_cvt_pk_f16_f32 v5, v32, v33
	ds_write_b128 v82, v[58:61] offset:49216
	v_cvt_pk_f16_f32 v58, v74, v75
	v_cvt_pk_f16_f32 v59, v76, v77
	v_cvt_pk_f16_f32 v60, v78, v79
	v_cvt_pk_f16_f32 v61, v80, v81
	ds_write_b128 v82, v[2:5] offset:49360
	v_mul_u32_u24_e32 v4, 0x110, v160
	ds_write_b128 v82, v[58:61] offset:49232
	v_add3_u32 v1, v1, v4, v154
	ds_read_b128 v[4:7], v1 offset:49152
	v_or3_b32 v2, v159, s55, v160
	v_mov_b32_e32 v3, v0
	v_lshlrev_b64 v[2:3], 12, v[2:3]
	v_lshlrev_b32_e32 v8, 7, v206
	v_lshl_add_u64 v[2:3], s[18:19], 0, v[2:3]
	v_ashrrev_i32_e32 v9, 31, v8
	v_lshl_add_u64 v[2:3], v[8:9], 1, v[2:3]
	ds_read_b128 v[8:11], v1 offset:50240
	s_waitcnt lgkmcnt(1)
	v_cvt_f32_f16_e32 v12, v4
	v_cvt_f32_f16_sdwa v13, v4 dst_sel:DWORD dst_unused:UNUSED_PAD src0_sel:WORD_1
	s_waitcnt vmcnt(7)
	v_lshlrev_b32_e32 v14, 16, v146
	v_and_b32_e32 v15, 0xffff0000, v146
	v_lshl_add_u64 v[2:3], v[2:3], 0, v[154:155]
	v_pk_mul_f32 v[12:13], v[14:15], v[12:13]
	v_cvt_f32_f16_e32 v14, v5
	v_cvt_f32_f16_sdwa v15, v5 dst_sel:DWORD dst_unused:UNUSED_PAD src0_sel:WORD_1
	v_cvt_pk_bf16_f32 v4, v12, v13
	v_lshlrev_b32_e32 v12, 16, v147
	v_and_b32_e32 v13, 0xffff0000, v147
	v_pk_mul_f32 v[12:13], v[12:13], v[14:15]
	v_cvt_f32_f16_e32 v14, v6
	v_cvt_f32_f16_sdwa v15, v6 dst_sel:DWORD dst_unused:UNUSED_PAD src0_sel:WORD_1
	v_cvt_pk_bf16_f32 v5, v12, v13
	v_lshlrev_b32_e32 v12, 16, v148
	v_and_b32_e32 v13, 0xffff0000, v148
	v_pk_mul_f32 v[12:13], v[12:13], v[14:15]
	v_cvt_f32_f16_e32 v14, v7
	v_cvt_f32_f16_sdwa v15, v7 dst_sel:DWORD dst_unused:UNUSED_PAD src0_sel:WORD_1
	v_cvt_pk_bf16_f32 v6, v12, v13
	v_lshlrev_b32_e32 v12, 16, v149
	v_and_b32_e32 v13, 0xffff0000, v149
	v_pk_mul_f32 v[12:13], v[12:13], v[14:15]
	v_add_co_u32_e32 v16, vcc, s16, v2
	v_cvt_pk_bf16_f32 v7, v12, v13
	global_store_dwordx4 v[2:3], v[4:7], off
	s_waitcnt lgkmcnt(0)
	v_cvt_f32_f16_e32 v12, v8
	v_cvt_f32_f16_sdwa v13, v8 dst_sel:DWORD dst_unused:UNUSED_PAD src0_sel:WORD_1
	v_cvt_f32_f16_e32 v6, v9
	v_cvt_f32_f16_sdwa v7, v9 dst_sel:DWORD dst_unused:UNUSED_PAD src0_sel:WORD_1
	s_waitcnt vmcnt(7)
	v_lshlrev_b32_e32 v8, 16, v151
	v_and_b32_e32 v9, 0xffff0000, v151
	v_lshlrev_b32_e32 v4, 16, v150
	v_pk_mul_f32 v[6:7], v[8:9], v[6:7]
	v_cvt_f32_f16_e32 v8, v10
	v_cvt_f32_f16_sdwa v9, v10 dst_sel:DWORD dst_unused:UNUSED_PAD src0_sel:WORD_1
	v_and_b32_e32 v5, 0xffff0000, v150
	v_pk_mul_f32 v[4:5], v[4:5], v[12:13]
	v_lshlrev_b32_e32 v10, 16, v153
	v_cvt_pk_bf16_f32 v4, v4, v5
	v_cvt_pk_bf16_f32 v5, v6, v7
	v_lshlrev_b32_e32 v6, 16, v152
	v_and_b32_e32 v7, 0xffff0000, v152
	v_pk_mul_f32 v[6:7], v[6:7], v[8:9]
	v_cvt_f32_f16_e32 v8, v11
	v_cvt_f32_f16_sdwa v9, v11 dst_sel:DWORD dst_unused:UNUSED_PAD src0_sel:WORD_1
	v_and_b32_e32 v11, 0xffff0000, v153
	v_cvt_pk_bf16_f32 v6, v6, v7
	v_addc_co_u32_e32 v17, vcc, 0, v3, vcc
	v_pk_mul_f32 v[8:9], v[10:11], v[8:9]
	ds_read_b128 v[12:15], v1 offset:52416
	v_cvt_pk_bf16_f32 v7, v8, v9
	ds_read_b128 v[8:11], v1 offset:51328
	global_store_dwordx4 v[16:17], v[4:7], off
	s_waitcnt lgkmcnt(0)
	v_cvt_f32_f16_e32 v18, v8
	v_cvt_f32_f16_e32 v6, v9
	v_cvt_f32_f16_sdwa v7, v9 dst_sel:DWORD dst_unused:UNUSED_PAD src0_sel:WORD_1
	v_cvt_f32_f16_sdwa v19, v8 dst_sel:DWORD dst_unused:UNUSED_PAD src0_sel:WORD_1
	s_waitcnt vmcnt(7)
	v_lshlrev_b32_e32 v8, 16, v55
	v_and_b32_e32 v9, 0xffff0000, v55
	v_pk_mul_f32 v[6:7], v[8:9], v[6:7]
	v_cvt_f32_f16_e32 v8, v10
	v_cvt_f32_f16_sdwa v9, v10 dst_sel:DWORD dst_unused:UNUSED_PAD src0_sel:WORD_1
	v_lshlrev_b32_e32 v4, 16, v54
	v_and_b32_e32 v5, 0xffff0000, v54
	v_pk_mul_f32 v[4:5], v[4:5], v[18:19]
	v_lshlrev_b32_e32 v10, 16, v57
	v_cvt_pk_bf16_f32 v4, v4, v5
	v_cvt_pk_bf16_f32 v5, v6, v7
	v_lshlrev_b32_e32 v6, 16, v56
	v_and_b32_e32 v7, 0xffff0000, v56
	v_pk_mul_f32 v[6:7], v[6:7], v[8:9]
	v_cvt_f32_f16_e32 v8, v11
	v_cvt_f32_f16_sdwa v9, v11 dst_sel:DWORD dst_unused:UNUSED_PAD src0_sel:WORD_1
	v_and_b32_e32 v11, 0xffff0000, v57
	v_cvt_pk_bf16_f32 v6, v6, v7
	v_pk_mul_f32 v[8:9], v[10:11], v[8:9]
	s_nop 0
	v_cvt_pk_bf16_f32 v7, v8, v9
	v_add_co_u32_e32 v8, vcc, s41, v2
	v_cvt_f32_f16_e32 v10, v12
	s_nop 0
	v_addc_co_u32_e32 v9, vcc, 0, v3, vcc
	global_store_dwordx4 v[8:9], v[4:7], off
	v_cvt_f32_f16_sdwa v11, v12 dst_sel:DWORD dst_unused:UNUSED_PAD src0_sel:WORD_1
	s_waitcnt vmcnt(7)
	v_lshlrev_b32_e32 v8, 16, v51
	v_cvt_f32_f16_e32 v6, v13
	v_cvt_f32_f16_sdwa v7, v13 dst_sel:DWORD dst_unused:UNUSED_PAD src0_sel:WORD_1
	v_and_b32_e32 v9, 0xffff0000, v51
	v_lshlrev_b32_e32 v4, 16, v50
	v_and_b32_e32 v5, 0xffff0000, v50
	v_pk_mul_f32 v[6:7], v[8:9], v[6:7]
	v_cvt_f32_f16_e32 v8, v14
	v_cvt_f32_f16_sdwa v9, v14 dst_sel:DWORD dst_unused:UNUSED_PAD src0_sel:WORD_1
	v_pk_mul_f32 v[4:5], v[4:5], v[10:11]
	v_lshlrev_b32_e32 v10, 16, v53
	v_cvt_pk_bf16_f32 v4, v4, v5
	v_cvt_pk_bf16_f32 v5, v6, v7
	v_lshlrev_b32_e32 v6, 16, v52
	v_and_b32_e32 v7, 0xffff0000, v52
	v_pk_mul_f32 v[6:7], v[6:7], v[8:9]
	v_cvt_f32_f16_e32 v8, v15
	v_cvt_f32_f16_sdwa v9, v15 dst_sel:DWORD dst_unused:UNUSED_PAD src0_sel:WORD_1
	v_and_b32_e32 v11, 0xffff0000, v53
	v_cvt_pk_bf16_f32 v6, v6, v7
	v_add_co_u32_e32 v16, vcc, s50, v2
	v_pk_mul_f32 v[8:9], v[10:11], v[8:9]
	s_nop 0
	v_addc_co_u32_e32 v17, vcc, 0, v3, vcc
	v_cvt_pk_bf16_f32 v7, v8, v9
	ds_read_b128 v[8:11], v1 offset:53504
	ds_read_b128 v[12:15], v1 offset:54592
	global_store_dwordx4 v[16:17], v[4:7], off
	s_waitcnt lgkmcnt(1)
	v_cvt_f32_f16_e32 v18, v8
	v_cvt_f32_f16_e32 v6, v9
	v_cvt_f32_f16_sdwa v7, v9 dst_sel:DWORD dst_unused:UNUSED_PAD src0_sel:WORD_1
	v_cvt_f32_f16_sdwa v19, v8 dst_sel:DWORD dst_unused:UNUSED_PAD src0_sel:WORD_1
	s_waitcnt vmcnt(7)
	v_lshlrev_b32_e32 v8, 16, v47
	v_and_b32_e32 v9, 0xffff0000, v47
	v_pk_mul_f32 v[6:7], v[8:9], v[6:7]
	v_cvt_f32_f16_e32 v8, v10
	v_cvt_f32_f16_sdwa v9, v10 dst_sel:DWORD dst_unused:UNUSED_PAD src0_sel:WORD_1
	v_lshlrev_b32_e32 v4, 16, v46
	v_and_b32_e32 v5, 0xffff0000, v46
	v_pk_mul_f32 v[4:5], v[4:5], v[18:19]
	v_lshlrev_b32_e32 v10, 16, v49
	v_cvt_pk_bf16_f32 v4, v4, v5
	v_cvt_pk_bf16_f32 v5, v6, v7
	v_lshlrev_b32_e32 v6, 16, v48
	v_and_b32_e32 v7, 0xffff0000, v48
	v_pk_mul_f32 v[6:7], v[6:7], v[8:9]
	v_cvt_f32_f16_e32 v8, v11
	v_cvt_f32_f16_sdwa v9, v11 dst_sel:DWORD dst_unused:UNUSED_PAD src0_sel:WORD_1
	v_and_b32_e32 v11, 0xffff0000, v49
	v_cvt_pk_bf16_f32 v6, v6, v7
	v_pk_mul_f32 v[8:9], v[10:11], v[8:9]
	s_nop 0
	v_cvt_pk_bf16_f32 v7, v8, v9
	v_add_co_u32_e32 v8, vcc, s51, v2
	s_waitcnt lgkmcnt(0)
	v_cvt_f32_f16_e32 v10, v12
	v_addc_co_u32_e32 v9, vcc, 0, v3, vcc
	global_store_dwordx4 v[8:9], v[4:7], off
	v_cvt_f32_f16_sdwa v11, v12 dst_sel:DWORD dst_unused:UNUSED_PAD src0_sel:WORD_1
	s_waitcnt vmcnt(7)
	v_lshlrev_b32_e32 v8, 16, v43
	v_cvt_f32_f16_e32 v6, v13
	v_cvt_f32_f16_sdwa v7, v13 dst_sel:DWORD dst_unused:UNUSED_PAD src0_sel:WORD_1
	v_and_b32_e32 v9, 0xffff0000, v43
	v_lshlrev_b32_e32 v4, 16, v42
	v_and_b32_e32 v5, 0xffff0000, v42
	v_pk_mul_f32 v[6:7], v[8:9], v[6:7]
	v_cvt_f32_f16_e32 v8, v14
	v_cvt_f32_f16_sdwa v9, v14 dst_sel:DWORD dst_unused:UNUSED_PAD src0_sel:WORD_1
	v_pk_mul_f32 v[4:5], v[4:5], v[10:11]
	v_lshlrev_b32_e32 v10, 16, v45
	v_cvt_pk_bf16_f32 v4, v4, v5
	v_cvt_pk_bf16_f32 v5, v6, v7
	v_lshlrev_b32_e32 v6, 16, v44
	v_and_b32_e32 v7, 0xffff0000, v44
	v_pk_mul_f32 v[6:7], v[6:7], v[8:9]
	v_cvt_f32_f16_e32 v8, v15
	v_cvt_f32_f16_sdwa v9, v15 dst_sel:DWORD dst_unused:UNUSED_PAD src0_sel:WORD_1
	v_and_b32_e32 v11, 0xffff0000, v45
	v_cvt_pk_bf16_f32 v6, v6, v7
	v_add_co_u32_e32 v16, vcc, s52, v2
	v_pk_mul_f32 v[8:9], v[10:11], v[8:9]
	s_nop 0
	v_addc_co_u32_e32 v17, vcc, 0, v3, vcc
	v_cvt_pk_bf16_f32 v7, v8, v9
	ds_read_b128 v[8:11], v1 offset:55680
	ds_read_b128 v[12:15], v1 offset:56768
	global_store_dwordx4 v[16:17], v[4:7], off
	s_waitcnt lgkmcnt(1)
	v_cvt_f32_f16_e32 v18, v8
	v_cvt_f32_f16_e32 v6, v9
	v_cvt_f32_f16_sdwa v7, v9 dst_sel:DWORD dst_unused:UNUSED_PAD src0_sel:WORD_1
	v_cvt_f32_f16_sdwa v19, v8 dst_sel:DWORD dst_unused:UNUSED_PAD src0_sel:WORD_1
	s_waitcnt vmcnt(7)
	v_lshlrev_b32_e32 v8, 16, v39
	v_and_b32_e32 v9, 0xffff0000, v39
	v_pk_mul_f32 v[6:7], v[8:9], v[6:7]
	v_cvt_f32_f16_e32 v8, v10
	v_cvt_f32_f16_sdwa v9, v10 dst_sel:DWORD dst_unused:UNUSED_PAD src0_sel:WORD_1
	v_lshlrev_b32_e32 v4, 16, v38
	v_and_b32_e32 v5, 0xffff0000, v38
	v_pk_mul_f32 v[4:5], v[4:5], v[18:19]
	v_lshlrev_b32_e32 v10, 16, v41
	v_cvt_pk_bf16_f32 v4, v4, v5
	v_cvt_pk_bf16_f32 v5, v6, v7
	v_lshlrev_b32_e32 v6, 16, v40
	v_and_b32_e32 v7, 0xffff0000, v40
	v_pk_mul_f32 v[6:7], v[6:7], v[8:9]
	v_cvt_f32_f16_e32 v8, v11
	v_cvt_f32_f16_sdwa v9, v11 dst_sel:DWORD dst_unused:UNUSED_PAD src0_sel:WORD_1
	v_and_b32_e32 v11, 0xffff0000, v41
	v_cvt_pk_bf16_f32 v6, v6, v7
	v_pk_mul_f32 v[8:9], v[10:11], v[8:9]
	s_nop 0
	v_cvt_pk_bf16_f32 v7, v8, v9
	v_add_co_u32_e32 v8, vcc, s53, v2
	s_waitcnt lgkmcnt(0)
	v_cvt_f32_f16_e32 v10, v12
	v_addc_co_u32_e32 v9, vcc, 0, v3, vcc
	global_store_dwordx4 v[8:9], v[4:7], off
	v_cvt_f32_f16_sdwa v11, v12 dst_sel:DWORD dst_unused:UNUSED_PAD src0_sel:WORD_1
	s_waitcnt vmcnt(7)
	v_lshlrev_b32_e32 v8, 16, v35
	v_cvt_f32_f16_e32 v6, v13
	v_cvt_f32_f16_sdwa v7, v13 dst_sel:DWORD dst_unused:UNUSED_PAD src0_sel:WORD_1
	v_and_b32_e32 v9, 0xffff0000, v35
	v_lshlrev_b32_e32 v4, 16, v34
	v_and_b32_e32 v5, 0xffff0000, v34
	v_pk_mul_f32 v[6:7], v[8:9], v[6:7]
	v_cvt_f32_f16_e32 v8, v14
	v_cvt_f32_f16_sdwa v9, v14 dst_sel:DWORD dst_unused:UNUSED_PAD src0_sel:WORD_1
	v_pk_mul_f32 v[4:5], v[4:5], v[10:11]
	v_lshlrev_b32_e32 v10, 16, v37
	v_cvt_pk_bf16_f32 v4, v4, v5
	v_cvt_pk_bf16_f32 v5, v6, v7
	v_lshlrev_b32_e32 v6, 16, v36
	v_and_b32_e32 v7, 0xffff0000, v36
	v_pk_mul_f32 v[6:7], v[6:7], v[8:9]
	v_cvt_f32_f16_e32 v8, v15
	v_cvt_f32_f16_sdwa v9, v15 dst_sel:DWORD dst_unused:UNUSED_PAD src0_sel:WORD_1
	v_and_b32_e32 v11, 0xffff0000, v37
	v_add_co_u32_e32 v2, vcc, 0x1c000, v2
	v_pk_mul_f32 v[8:9], v[10:11], v[8:9]
	v_cvt_pk_bf16_f32 v6, v6, v7
	v_cvt_pk_bf16_f32 v7, v8, v9
	v_addc_co_u32_e32 v3, vcc, 0, v3, vcc
	global_store_dwordx4 v[2:3], v[4:7], off
